# first grid barrier: 16-word arrival scan issued as 16 loads in flight instead of 16 dependent round trips
# baseline (speedup 1.0000x reference)
; DI unsigned xb_ld(unsigned* p)              { return __hip_atomic_load(p, __ATOMIC_RELAXED, __HIP_MEMORY_SCOPE_AGENT); }
; DI void xcd_barrier_complete(unsigned* bar, unsigned x, unsigned& nloc, unsigned& nx) {
;     const unsigned G = gridDim.x;
;     unsigned sum, cnt, mine, sp = 0u;
;     for (;;) {
;         sum = 0u; cnt = 0u; mine = 0u;
; #pragma unroll
;         for (unsigned j = 0; j < 16; ++j) { const unsigned c = xb_ld(&bar[XB_XCNT(j)]); sum += c; cnt += (c > 0u) ? 1u : 0u; mine = (j == x) ? c : mine; }
;         if (sum == G) break;
;         __builtin_amdgcn_s_sleep(1);
;         if ((++sp & 255u) == 0u) { if (xb_ld(&bar[XB_TMO])) break; if (sp > XB_SPIN_CAP) { atomicAdd(&bar[XB_TMO], 1u); break; } }
;     }
.LBB0_79:
	v_readlane_b32 s6, v239, 8
	v_readlane_b32 s7, v239, 9
	s_mov_b64 s[8:9], -1
	s_nop 3
	global_load_dword v0, v1, s[6:7] sc1
	v_readlane_b32 s6, v239, 10
	v_readlane_b32 s7, v239, 11
	s_waitcnt lgkmcnt(0)
	s_nop 3
	global_load_dword v2, v1, s[6:7] sc1
	v_readlane_b32 s6, v239, 12
	v_readlane_b32 s7, v239, 13
	s_nop 4
	global_load_dword v3, v1, s[6:7] sc1
	v_readlane_b32 s6, v239, 14
	v_readlane_b32 s7, v239, 15
	s_nop 4
	global_load_dword v4, v1, s[6:7] sc1
	v_readlane_b32 s6, v239, 16
	v_readlane_b32 s7, v239, 17
	s_nop 4
	global_load_dword v5, v1, s[6:7] sc1
	v_readlane_b32 s6, v239, 18
	v_readlane_b32 s7, v239, 19
	s_nop 4
	global_load_dword v6, v1, s[6:7] sc1
	v_readlane_b32 s6, v239, 20
	v_readlane_b32 s7, v239, 21
	s_nop 4
	global_load_dword v7, v1, s[6:7] sc1
	v_readlane_b32 s6, v239, 22
	v_readlane_b32 s7, v239, 23
	s_nop 4
	global_load_dword v8, v1, s[6:7] sc1
	v_readlane_b32 s6, v239, 24
	v_readlane_b32 s7, v239, 25
	s_nop 4
	global_load_dword v9, v1, s[6:7] sc1
	v_readlane_b32 s6, v239, 26
	v_readlane_b32 s7, v239, 27
	s_nop 4
	global_load_dword v10, v1, s[6:7] sc1
	v_readlane_b32 s6, v239, 28
	v_readlane_b32 s7, v239, 29
	s_nop 4
	global_load_dword v11, v1, s[6:7] sc1
	v_readlane_b32 s6, v239, 30
	v_readlane_b32 s7, v239, 31
	s_nop 4
	global_load_dword v12, v1, s[6:7] sc1
	v_readlane_b32 s6, v239, 32
	v_readlane_b32 s7, v239, 33
	s_nop 4
	global_load_dword v13, v1, s[6:7] sc1
	v_readlane_b32 s6, v239, 34
	v_readlane_b32 s7, v239, 35
	s_nop 4
	global_load_dword v14, v1, s[6:7] sc1
	v_readlane_b32 s6, v239, 36
	v_readlane_b32 s7, v239, 37
	s_nop 4
	global_load_dword v15, v1, s[6:7] sc1
	v_readlane_b32 s6, v239, 38
	v_readlane_b32 s7, v239, 39
	s_nop 4
	global_load_dword v16, v1, s[6:7] sc1
	s_mov_b64 s[6:7], -1
	s_waitcnt vmcnt(0)
	v_add_u32_e32 v17, v2, v0
	v_add_u32_e32 v17, v17, v3
	v_add_u32_e32 v17, v17, v4
	v_add_u32_e32 v17, v17, v5
	v_add_u32_e32 v17, v17, v6
	v_add_u32_e32 v17, v17, v7
	v_add_u32_e32 v17, v17, v8
	v_add_u32_e32 v17, v17, v9
	v_add_u32_e32 v17, v17, v10
	v_add_u32_e32 v17, v17, v11
	v_add_u32_e32 v17, v17, v12
	v_add_u32_e32 v17, v17, v13
	v_add_u32_e32 v17, v17, v14
	v_add_u32_e32 v17, v17, v15
	v_add_u32_e32 v17, v17, v16
	v_cmp_eq_u32_e32 vcc, s99, v17
	s_cbranch_vccnz .LBB0_78
	s_and_b32 s6, s23, 0xff
	s_cmp_eq_u32 s6, 0
	s_mov_b64 s[6:7], -1
	s_mov_b64 s[10:11], -1
	s_sleep 1
	s_cbranch_scc0 .LBB0_83
	v_readlane_b32 s6, v239, 6
	v_readlane_b32 s7, v239, 7
	s_nop 4
	global_load_dword v17, v1, s[6:7] sc1
	s_waitcnt vmcnt(0)
	v_cmp_eq_u32_e32 vcc, 0, v17
	s_cbranch_vccnz .LBB0_85
	s_mov_b64 s[10:11], 0
	s_mov_b64 s[6:7], -1
